# prep weight-conversion loops: next item's loads stay in flight across the transpose and stores (no per-item drain)
# speedup vs baseline: 1.0643x; 1.0007x over previous
; #define LAS __attribute__((address_space(3)))
; __device__ __forceinline__ TItem titem(const Params& p, int l, int r, int lane) {
;     const float* W; half_t* WT; int N, ldt, koff = 0;
;     unsigned char* ws = p.ws;
;     const bool bf = (r < I_IN) ? INPROJ_BF16 : TAIL_BF16;
;     if (r < I_IN) { W = p.w_in + (size_t)l * DM * NIN; N = NIN; WT = (half_t*)(ws + WS_WIN + l * SZ_WIN); ldt = DM; }
;     else { r -= I_IN; N = DM;
;         if (r < I_SQ) { W = p.w_ret_o + (size_t)l * DM * DM; WT = (half_t*)(ws + WS_WMRG + l * SZ_WMRG); ldt = 4096; }
;         else if (r < 2 * I_SQ) { r -= I_SQ; W = p.w_swa_o + (size_t)l * DM * DM; WT = (half_t*)(ws + WS_WMRG + l * SZ_WMRG); ldt = 4096; koff = 2048; }
;         else { r -= 2 * I_SQ; W = p.w_out + (size_t)l * DM * DM; WT = (half_t*)(ws + WS_WOUT + l * SZ_WOUT); ldt = DM; } }
;     const int nblk = N >> 6, kb = r / nblk, nb = r - kb * nblk, k0 = kb * 32, n0 = nb * 64;
;     TItem t; t.N = N; t.ldt = ldt; t.bf = bf;
;     t.src = W + (size_t)(k0 + (lane >> 4)) * N + n0 + (lane & 15) * 4;
;     t.dst = WT + (size_t)(n0 + (lane >> 2)) * ldt + koff + k0 + 8 * (lane & 3);
;     return t;
; }
; __device__ __forceinline__ void tload(const TItem& t, f32x4 (&v)[8]) {
; #pragma unroll
;     for (int i = 0; i < 8; ++i) v[i] = *(const f32x4*)(t.src + (size_t)(4 * i) * t.N);
; __device__ __forceinline__ void convert_range(const Params& p, int l, int lo, int hi, LAS float* scr, int gw, int NGW, int lane) {
;     int it = lo + gw;
;     if (it >= hi) return;
;     f32x4 cur[8], nxt[8];
;     TItem tc = titem(p, l, it, lane);
;     tload(tc, cur);
.LBB0_49:
	s_lshr_b32 s14, s0, 6
	v_cvt_f32_ubyte0_e32 v2, s14
	v_rcp_iflag_f32_e32 v2, v2
	s_sub_i32 s19, 0, s14
	s_abs_i32 s18, s7
	s_ashr_i32 s15, s7, 31
	v_mul_f32_e32 v2, 0x4f7ffffe, v2
	v_cvt_u32_f32_e32 v2, v2
	v_lshrrev_b32_e32 v74, 4, v1
	v_lshlrev_b32_e32 v4, 2, v1
	v_and_b32_e32 v34, 60, v4
	v_readfirstlane_b32 s20, v2
	s_mul_i32 s19, s19, s20
	s_mul_hi_u32 s19, s20, s19
	s_add_i32 s20, s20, s19
	s_mul_hi_u32 s19, s18, s20
	s_mul_i32 s20, s19, s14
	s_sub_i32 s18, s18, s20
	s_add_i32 s21, s19, 1
	s_sub_i32 s20, s18, s14
	s_cmp_ge_u32 s18, s14
	s_cselect_b32 s19, s21, s19
	s_cselect_b32 s18, s20, s18
	s_add_i32 s20, s19, 1
	s_cmp_ge_u32 s18, s14
	s_cselect_b32 s18, s20, s19
	s_xor_b32 s18, s18, s15
	s_sub_i32 s15, s18, s15
	s_mul_i32 s14, s15, s14
	s_sub_i32 s7, s7, s14
	s_lshl_b32 s14, s15, 5
	v_or_b32_e32 v2, s14, v74
	s_lshl_b32 s18, s7, 6
	v_mad_i64_i32 v[2:3], s[20:21], v2, s0, 0
	v_lshl_add_u64 v[2:3], v[2:3], 2, s[12:13]
	s_ashr_i32 s19, s18, 31
	v_lshl_add_u64 v[2:3], s[18:19], 2, v[2:3]
	v_mov_b32_e32 v67, 0
	v_lshlrev_b32_e32 v66, 2, v34
	s_mov_b32 s1, 0
	v_lshl_add_u64 v[2:3], v[2:3], 0, v[66:67]
	s_lshl_b32 s0, s0, 4
	v_lshl_add_u64 v[4:5], v[2:3], 0, s[0:1]
	global_load_dwordx4 v[26:29], v[2:3], off
	global_load_dwordx4 v[22:25], v[4:5], off
	v_lshl_add_u64 v[2:3], v[4:5], 0, s[0:1]
	v_lshl_add_u64 v[4:5], v[2:3], 0, s[0:1]
	global_load_dwordx4 v[18:21], v[2:3], off
	global_load_dwordx4 v[14:17], v[4:5], off
	v_lshl_add_u64 v[2:3], v[4:5], 0, s[0:1]
	v_lshl_add_u64 v[4:5], v[2:3], 0, s[0:1]
	global_load_dwordx4 v[10:13], v[2:3], off
	global_load_dwordx4 v[6:9], v[4:5], off
	v_lshl_add_u64 v[2:3], v[4:5], 0, s[0:1]
	v_lshl_add_u64 v[30:31], v[2:3], 0, s[0:1]
	global_load_dwordx4 v[2:5], v[2:3], off
	s_nop 0
	global_load_dwordx4 v[30:33], v[30:31], off
	v_lshrrev_b32_e32 v75, 2, v1
	v_or_b32_e32 v35, s18, v75
	s_mul_i32 s0, s19, s6
	v_mad_u64_u32 v[36:37], s[12:13], v35, s6, 0
	v_add_u32_e32 v37, s0, v37
	s_ashr_i32 s15, s14, 31
	v_lshl_add_u64 v[36:37], v[36:37], 1, s[8:9]
	s_add_u32 s8, s66, 0x13000000
	v_lshlrev_b32_e32 v35, 3, v1
	s_addc_u32 s9, s67, 0
	v_lshl_add_u64 v[36:37], s[10:11], 1, v[36:37]
	v_and_b32_e32 v38, 24, v35
	s_add_u32 s10, s66, 0xf000000
	v_lshl_add_u64 v[36:37], s[14:15], 1, v[36:37]
	v_lshlrev_b32_e32 v40, 1, v38
	v_mov_b32_e32 v41, v67
	s_addc_u32 s11, s67, 0
	s_lshl_b32 s0, s2, 3
	v_lshl_add_u64 v[70:71], v[36:37], 0, v[40:41]
	v_and_b32_e32 v37, 60, v1
	s_add_i32 s0, s40, s0
	s_lshl_b32 s7, s28, 3
	v_add_u32_e32 v35, s36, v66
	v_mul_u32_u24_e32 v36, 0x110, v74
	v_add_u32_e32 v37, s36, v37
	v_mul_u32_u24_e32 v39, 0x110, v38
	s_add_i32 s0, s0, s7
	s_lshl_b32 s7, s26, 4
	s_sub_i32 s30, s0, s7
	v_lshlrev_b32_e32 v66, 2, v34
	v_lshlrev_b32_e32 v68, 1, v38
	v_add_u32_e32 v76, v35, v36
	v_add_u32_e32 v77, v37, v39
	s_mov_b32 s31, s27
	v_mov_b64_e32 v[72:73], v[70:71]
	s_mov_b32 s99, 0
	s_branch .LBB0_51

; #define LAS __attribute__((address_space(3)))
; __device__ __forceinline__ TItem titem(const Params& p, int l, int r, int lane) {
;     const float* W; half_t* WT; int N, ldt, koff = 0;
;     unsigned char* ws = p.ws;
;     const bool bf = (r < I_IN) ? INPROJ_BF16 : TAIL_BF16;
;     if (r < I_IN) { W = p.w_in + (size_t)l * DM * NIN; N = NIN; WT = (half_t*)(ws + WS_WIN + l * SZ_WIN); ldt = DM; }
;     else { r -= I_IN; N = DM;
;         if (r < I_SQ) { W = p.w_ret_o + (size_t)l * DM * DM; WT = (half_t*)(ws + WS_WMRG + l * SZ_WMRG); ldt = 4096; }
;         else if (r < 2 * I_SQ) { r -= I_SQ; W = p.w_swa_o + (size_t)l * DM * DM; WT = (half_t*)(ws + WS_WMRG + l * SZ_WMRG); ldt = 4096; koff = 2048; }
;         else { r -= 2 * I_SQ; W = p.w_out + (size_t)l * DM * DM; WT = (half_t*)(ws + WS_WOUT + l * SZ_WOUT); ldt = DM; } }
;     const int nblk = N >> 6, kb = r / nblk, nb = r - kb * nblk, k0 = kb * 32, n0 = nb * 64;
;     TItem t; t.N = N; t.ldt = ldt; t.bf = bf;
;     t.src = W + (size_t)(k0 + (lane >> 4)) * N + n0 + (lane & 15) * 4;
;     t.dst = WT + (size_t)(n0 + (lane >> 2)) * ldt + koff + k0 + 8 * (lane & 3);
;     return t;
; }
; __device__ __forceinline__ void tload(const TItem& t, f32x4 (&v)[8]) {
; #pragma unroll
;     for (int i = 0; i < 8; ++i) v[i] = *(const f32x4*)(t.src + (size_t)(4 * i) * t.N);
; __device__ __forceinline__ void tstore(const TItem& t, const f32x4 (&v)[8], LAS float* scr, int lane) {
;     const int rr = lane >> 4, c4 = (lane & 15) * 4;
; #pragma unroll
;     for (int i = 0; i < 8; ++i) *(LAS f32x4*)(scr + (4 * i + rr) * 68 + c4) = v[i];
; __device__ __forceinline__ void convert_range(const Params& p, int l, int lo, int hi, LAS float* scr, int gw, int NGW, int lane) {
;     ...
;         const int itn = it + NGW; const bool more = itn < hi;
;         TItem tn = tc;
;         if (more) { tn = titem(p, l, itn, lane); tload(tn, nxt); }
;         tstore(tc, cur, scr, lane);
.LBB0_64:
	s_lshr_b32 s24, s7, 6
	v_cvt_f32_ubyte0_e32 v34, s24
	v_rcp_iflag_f32_e32 v34, v34
	s_sub_i32 s38, 0, s24
	s_abs_i32 s37, s0
	s_ashr_i32 s25, s0, 31
	v_mul_f32_e32 v34, 0x4f7ffffe, v34
	v_cvt_u32_f32_e32 v34, v34
	s_nop 0
	v_readfirstlane_b32 s39, v34
	s_mul_i32 s38, s38, s39
	s_mul_hi_u32 s38, s39, s38
	s_add_i32 s39, s39, s38
	s_mul_hi_u32 s38, s37, s39
	s_mul_i32 s39, s38, s24
	s_sub_i32 s37, s37, s39
	s_add_i32 s41, s38, 1
	s_sub_i32 s39, s37, s24
	s_cmp_ge_u32 s37, s24
	s_cselect_b32 s38, s41, s38
	s_cselect_b32 s37, s39, s37
	s_add_i32 s39, s38, 1
	s_cmp_ge_u32 s37, s24
	s_cselect_b32 s37, s39, s38
	s_xor_b32 s37, s37, s25
	s_sub_i32 s25, s37, s25
	s_mul_i32 s37, s25, s24
	s_lshl_b32 s24, s25, 5
	s_sub_i32 s0, s0, s37
	v_or_b32_e32 v34, s24, v74
	s_lshl_b32 s38, s0, 6
	v_mad_i64_i32 v[34:35], s[42:43], v34, s7, 0
	v_lshl_add_u64 v[34:35], v[34:35], 2, s[20:21]
	s_ashr_i32 s39, s38, 31
	v_lshl_add_u64 v[34:35], s[38:39], 2, v[34:35]
	v_lshl_add_u64 v[34:35], v[34:35], 0, v[66:67]
	s_lshl_b32 s0, s7, 4
	v_lshl_add_u64 v[42:43], v[34:35], 0, s[0:1]
	global_load_dwordx4 v[38:41], v[34:35], off
	s_nop 0
	global_load_dwordx4 v[34:37], v[42:43], off
	v_lshl_add_u64 v[42:43], v[42:43], 0, s[0:1]
	v_lshl_add_u64 v[50:51], v[42:43], 0, s[0:1]
	global_load_dwordx4 v[46:49], v[42:43], off
	s_nop 0
	global_load_dwordx4 v[42:45], v[50:51], off
	v_lshl_add_u64 v[50:51], v[50:51], 0, s[0:1]
	v_lshl_add_u64 v[58:59], v[50:51], 0, s[0:1]
	global_load_dwordx4 v[54:57], v[50:51], off
	s_nop 0
	global_load_dwordx4 v[50:53], v[58:59], off
	v_lshl_add_u64 v[58:59], v[58:59], 0, s[0:1]
	v_lshl_add_u64 v[60:61], v[58:59], 0, s[0:1]
	global_load_dwordx4 v[62:65], v[58:59], off
	s_nop 0
	global_load_dwordx4 v[58:61], v[60:61], off
	v_or_b32_e32 v69, s38, v75
	s_mul_i32 s0, s39, s35
	v_mad_u64_u32 v[72:73], s[20:21], v69, s35, 0
	v_add_u32_e32 v73, s0, v73
	v_lshl_add_u64 v[72:73], v[72:73], 1, s[18:19]
	v_lshl_add_u64 v[72:73], s[14:15], 1, v[72:73]
	s_ashr_i32 s25, s24, 31
	v_lshl_add_u64 v[72:73], s[24:25], 1, v[72:73]
	v_mov_b32_e32 v69, v67
	v_lshl_add_u64 v[72:73], v[72:73], 0, v[68:69]
	s_cmp_eq_u32 s99, 0
	s_cbranch_scc1 .Lcv_first_51
	s_waitcnt vmcnt(19)
	ds_write_b128 v76, v[26:29] offset:32768
	s_waitcnt vmcnt(18)
	ds_write_b128 v76, v[22:25] offset:33856
	s_waitcnt vmcnt(17)
	ds_write_b128 v76, v[18:21] offset:34944
	s_waitcnt vmcnt(16)
	ds_write_b128 v76, v[14:17] offset:36032
	s_waitcnt vmcnt(15)
	ds_write_b128 v76, v[10:13] offset:37120
	s_waitcnt vmcnt(14)
	ds_write_b128 v76, v[6:9] offset:38208
	s_waitcnt vmcnt(13)
	ds_write_b128 v76, v[2:5] offset:39296
	s_waitcnt vmcnt(12)
	ds_write_b128 v76, v[30:33] offset:40384
	s_branch .Lcv_join_51
.Lcv_first_51:
	s_waitcnt vmcnt(15)
	ds_write_b128 v76, v[26:29] offset:32768
	s_waitcnt vmcnt(14)
	ds_write_b128 v76, v[22:25] offset:33856
	s_waitcnt vmcnt(13)
	ds_write_b128 v76, v[18:21] offset:34944
	s_waitcnt vmcnt(12)
	ds_write_b128 v76, v[14:17] offset:36032
	s_waitcnt vmcnt(11)
	ds_write_b128 v76, v[10:13] offset:37120
	s_waitcnt vmcnt(10)
	ds_write_b128 v76, v[6:9] offset:38208
	s_waitcnt vmcnt(9)
	ds_write_b128 v76, v[2:5] offset:39296
	s_waitcnt vmcnt(8)
	ds_write_b128 v76, v[30:33] offset:40384
	s_branch .Lcv_join_51

; #define LAS __attribute__((address_space(3)))
; __device__ __forceinline__ void tstore(const TItem& t, const f32x4 (&v)[8], LAS float* scr, int lane) {
;     ...
;     asm volatile("s_waitcnt lgkmcnt(0)" ::: "memory");
;     const int c = lane & 3;
; #pragma unroll
;     for (int j = 0; j < 4; ++j) { const int n = (lane >> 2) + 16 * j; const LAS float* s = scr + (8 * c) * 68 + n;
;         h8 o;
; #pragma unroll
;         for (int e = 0; e < 8; ++e) o[e] = op16(s[e * 68], t.bf);
;         *(h8*)(t.dst + (size_t)(16 * j) * t.ldt) = o; }
;     asm volatile("s_waitcnt lgkmcnt(0)" ::: "memory");
; }
; __device__ __forceinline__ void convert_range(const Params& p, int l, int lo, int hi, LAS float* scr, int gw, int NGW, int lane) {
;     ...
;         tstore(tc, cur, scr, lane);
;         if (!more) break;
; #pragma unroll
;         for (int i = 0; i < 8; ++i) cur[i] = nxt[i];
;         tc = tn; it = itn;
.Lcv_join_51:
	s_waitcnt lgkmcnt(0)
	v_add_u32_e32 v22, 0x8000, v77
	v_add_u32_e32 v23, 0x8400, v77
	ds_read2_b32 v[6:7], v22 offset1:16
	ds_read2_b32 v[8:9], v22 offset0:136 offset1:152
	ds_read2_b32 v[10:11], v23 offset0:16 offset1:32
	ds_read2_b32 v[12:13], v23 offset0:152 offset1:168
	ds_read2_b32 v[14:15], v23 offset0:220 offset1:236
	ds_read2_b32 v[16:17], v23 offset0:84 offset1:100
	ds_read2_b32 v[18:19], v22 offset0:204 offset1:220
	ds_read2_b32 v[20:21], v22 offset0:68 offset1:84
	s_mov_b32 s7, s1
	s_waitcnt lgkmcnt(3)
	v_cvt_pk_bf16_f32 v5, v12, v14
	s_waitcnt lgkmcnt(2)
	v_cvt_pk_bf16_f32 v4, v10, v16
	s_waitcnt lgkmcnt(1)
	v_cvt_pk_bf16_f32 v3, v8, v18
	s_waitcnt lgkmcnt(0)
	v_cvt_pk_bf16_f32 v2, v6, v20
	global_store_dwordx4 v[70:71], v[2:5], off
	v_add_u32_e32 v16, 0x8600, v77
	s_lshl_b64 s[6:7], s[6:7], 5
	v_cvt_pk_bf16_f32 v5, v13, v15
	v_cvt_pk_bf16_f32 v4, v11, v17
	v_cvt_pk_bf16_f32 v3, v9, v19
	v_cvt_pk_bf16_f32 v2, v7, v21
	ds_read2_b32 v[8:9], v22 offset0:32 offset1:48
	ds_read2_b32 v[10:11], v22 offset0:168 offset1:184
	ds_read2_b32 v[12:13], v23 offset0:48 offset1:64
	ds_read2_b32 v[14:15], v23 offset0:184 offset1:200
	ds_read2_b32 v[16:17], v16 offset0:124 offset1:140
	ds_read2_b32 v[18:19], v23 offset0:116 offset1:132
	ds_read2_b32 v[20:21], v22 offset0:236 offset1:252
	ds_read2_b32 v[22:23], v22 offset0:100 offset1:116
	v_lshl_add_u64 v[6:7], v[70:71], 0, s[6:7]
	global_store_dwordx4 v[6:7], v[2:5], off
	v_lshl_add_u64 v[6:7], v[6:7], 0, s[6:7]
	s_andn2_b64 vcc, exec, s[12:13]
	s_waitcnt lgkmcnt(3)
	v_cvt_pk_bf16_f32 v5, v14, v16
	s_waitcnt lgkmcnt(2)
	v_cvt_pk_bf16_f32 v4, v12, v18
	s_waitcnt lgkmcnt(1)
	v_cvt_pk_bf16_f32 v3, v10, v20
	s_waitcnt lgkmcnt(0)
	v_cvt_pk_bf16_f32 v2, v8, v22
	global_store_dwordx4 v[6:7], v[2:5], off
	v_lshl_add_u64 v[6:7], v[6:7], 0, s[6:7]
	s_mov_b64 s[6:7], -1
	v_cvt_pk_bf16_f32 v5, v15, v17
	v_cvt_pk_bf16_f32 v4, v13, v19
	v_cvt_pk_bf16_f32 v3, v11, v21
	v_cvt_pk_bf16_f32 v2, v9, v23
	global_store_dwordx4 v[6:7], v[2:5], off
	s_waitcnt lgkmcnt(0)
	s_cbranch_vccnz .LBB0_50
	s_waitcnt vmcnt(4)
	s_mov_b32 s99, 1
	s_add_i32 s30, s30, s34
	s_mov_b64 s[6:7], 0
	v_mov_b32_e32 v5, v65
	v_mov_b32_e32 v4, v64
	v_mov_b32_e32 v3, v63
	v_mov_b32_e32 v2, v62
	v_mov_b32_e32 v9, v53
	v_mov_b32_e32 v8, v52
	v_mov_b32_e32 v7, v51
	v_mov_b32_e32 v6, v50
	v_mov_b32_e32 v13, v57
	v_mov_b32_e32 v12, v56
	v_mov_b32_e32 v11, v55
	v_mov_b32_e32 v10, v54
	v_mov_b32_e32 v17, v45
	v_mov_b32_e32 v16, v44
	v_mov_b32_e32 v15, v43
	v_mov_b32_e32 v14, v42
	v_mov_b32_e32 v21, v49
	v_mov_b32_e32 v20, v48
	v_mov_b32_e32 v19, v47
	v_mov_b32_e32 v18, v46
	v_mov_b32_e32 v25, v37
	v_mov_b32_e32 v24, v36
	v_mov_b32_e32 v23, v35
	v_mov_b32_e32 v22, v34
	v_mov_b32_e32 v29, v41
	v_mov_b32_e32 v28, v40
	v_mov_b32_e32 v27, v39
	v_mov_b32_e32 v26, v38
	s_branch .LBB0_50

; #define LAS __attribute__((address_space(3)))
; __device__ __forceinline__ TItem titem(const Params& p, int l, int r, int lane) {
;     const float* W; half_t* WT; int N, ldt, koff = 0;
;     unsigned char* ws = p.ws;
;     const bool bf = (r < I_IN) ? INPROJ_BF16 : TAIL_BF16;
;     if (r < I_IN) { W = p.w_in + (size_t)l * DM * NIN; N = NIN; WT = (half_t*)(ws + WS_WIN + l * SZ_WIN); ldt = DM; }
;     else { r -= I_IN; N = DM;
;         if (r < I_SQ) { W = p.w_ret_o + (size_t)l * DM * DM; WT = (half_t*)(ws + WS_WMRG + l * SZ_WMRG); ldt = 4096; }
;         else if (r < 2 * I_SQ) { r -= I_SQ; W = p.w_swa_o + (size_t)l * DM * DM; WT = (half_t*)(ws + WS_WMRG + l * SZ_WMRG); ldt = 4096; koff = 2048; }
;         else { r -= 2 * I_SQ; W = p.w_out + (size_t)l * DM * DM; WT = (half_t*)(ws + WS_WOUT + l * SZ_WOUT); ldt = DM; } }
;     const int nblk = N >> 6, kb = r / nblk, nb = r - kb * nblk, k0 = kb * 32, n0 = nb * 64;
;     TItem t; t.N = N; t.ldt = ldt; t.bf = bf;
;     t.src = W + (size_t)(k0 + (lane >> 4)) * N + n0 + (lane & 15) * 4;
;     t.dst = WT + (size_t)(n0 + (lane >> 2)) * ldt + koff + k0 + 8 * (lane & 3);
;     return t;
; }
; __device__ __forceinline__ void tload(const TItem& t, f32x4 (&v)[8]) {
; #pragma unroll
;     for (int i = 0; i < 8; ++i) v[i] = *(const f32x4*)(t.src + (size_t)(4 * i) * t.N);
; __device__ __forceinline__ void convert_range(const Params& p, int l, int lo, int hi, LAS float* scr, int gw, int NGW, int lane) {
;     int it = lo + gw;
;     if (it >= hi) return;
;     f32x4 cur[8], nxt[8];
;     TItem tc = titem(p, l, it, lane);
;     tload(tc, cur);
.LBB0_79:
	s_add_u32 s10, s10, s14
	s_addc_u32 s11, s11, s15
	s_add_u32 s12, s66, s12
	s_addc_u32 s13, s67, s13
	s_lshr_b32 s0, s7, 6
	v_cvt_f32_ubyte0_e32 v2, s0
	v_rcp_iflag_f32_e32 v2, v2
	s_sub_i32 s15, 0, s0
	s_abs_i32 s14, s27
	s_ashr_i32 s9, s27, 31
	v_mul_f32_e32 v2, 0x4f7ffffe, v2
	v_cvt_u32_f32_e32 v2, v2
	v_lshrrev_b32_e32 v74, 4, v1
	v_lshlrev_b32_e32 v4, 2, v1
	v_lshrrev_b32_e32 v75, 2, v1
	v_readfirstlane_b32 s18, v2
	s_mul_i32 s15, s15, s18
	s_mul_hi_u32 s15, s18, s15
	s_add_i32 s18, s18, s15
	s_mul_hi_u32 s15, s14, s18
	s_mul_i32 s18, s15, s0
	s_sub_i32 s14, s14, s18
	s_add_i32 s19, s15, 1
	s_sub_i32 s18, s14, s0
	s_cmp_ge_u32 s14, s0
	s_cselect_b32 s15, s19, s15
	s_cselect_b32 s14, s18, s14
	s_add_i32 s18, s15, 1
	s_cmp_ge_u32 s14, s0
	s_cselect_b32 s14, s18, s15
	s_xor_b32 s14, s14, s9
	s_sub_i32 s9, s14, s9
	s_mul_i32 s0, s9, s0
	s_sub_i32 s0, s27, s0
	s_lshl_b32 s14, s9, 5
	s_lshl_b32 s18, s0, 6
	v_or_b32_e32 v2, s14, v74
	v_mad_i64_i32 v[2:3], s[20:21], v2, s7, 0
	v_and_b32_e32 v34, 60, v4
	v_or_b32_e32 v4, s18, v75
	v_lshl_add_u64 v[2:3], v[2:3], 2, s[10:11]
	s_ashr_i32 s19, s18, 31
	v_mad_i64_i32 v[4:5], s[10:11], v4, s6, 0
	v_lshl_add_u64 v[2:3], s[18:19], 2, v[2:3]
	v_mov_b32_e32 v67, 0
	v_lshlrev_b32_e32 v66, 2, v34
	v_lshl_add_u64 v[4:5], v[4:5], 1, s[12:13]
	s_lshl_b32 s0, s8, 1
	v_lshl_add_u64 v[2:3], v[2:3], 0, v[66:67]
	v_lshl_add_u64 v[36:37], v[4:5], 0, s[0:1]
	s_lshl_b32 s0, s7, 4
	v_lshl_add_u64 v[4:5], v[2:3], 0, s[0:1]
	global_load_dwordx4 v[26:29], v[2:3], off
	global_load_dwordx4 v[22:25], v[4:5], off
	v_lshl_add_u64 v[2:3], v[4:5], 0, s[0:1]
	v_lshl_add_u64 v[4:5], v[2:3], 0, s[0:1]
	global_load_dwordx4 v[18:21], v[2:3], off
	global_load_dwordx4 v[14:17], v[4:5], off
	v_lshl_add_u64 v[2:3], v[4:5], 0, s[0:1]
	v_lshl_add_u64 v[4:5], v[2:3], 0, s[0:1]
	v_lshl_add_u64 v[30:31], v[4:5], 0, s[0:1]
	global_load_dwordx4 v[10:13], v[2:3], off
	global_load_dwordx4 v[6:9], v[4:5], off
	v_readlane_b32 s44, v252, 0
	global_load_dwordx4 v[2:5], v[30:31], off
	v_lshl_add_u64 v[30:31], v[30:31], 0, s[0:1]
	global_load_dwordx4 v[30:33], v[30:31], off
	s_ashr_i32 s15, s14, 31
	v_readlane_b32 s48, v252, 4
	v_readlane_b32 s49, v252, 5
	s_add_u32 s8, s48, 0x1000000
	v_readlane_b32 s46, v252, 2
	s_addc_u32 s9, s49, 0
	v_readlane_b32 s47, v252, 3
	s_add_u32 s10, s46, 0x1000000
	s_addc_u32 s11, s47, 0
	v_readlane_b32 s45, v252, 1
	s_add_u32 s12, s44, 0x1000000
	s_addc_u32 s13, s45, 0
	v_lshl_add_u64 v[36:37], s[14:15], 1, v[36:37]
	v_lshlrev_b32_e32 v35, 3, v1
	s_add_u32 s14, s90, 0x7800000
	v_and_b32_e32 v38, 24, v35
	s_addc_u32 s15, s91, 0
	s_lshl_b32 s0, s2, 3
	v_lshlrev_b32_e32 v40, 1, v38
	v_mov_b32_e32 v41, v67
	s_add_i32 s0, s40, s0
	s_lshl_b32 s7, s28, 3
	v_lshl_add_u64 v[70:71], v[36:37], 0, v[40:41]
	v_and_b32_e32 v37, 60, v1
	s_add_i32 s0, s0, s7
	s_lshl_b32 s7, s26, 4
	v_add_u32_e32 v35, s36, v66
	v_mul_u32_u24_e32 v36, 0x110, v74
	v_add_u32_e32 v37, s36, v37
	v_mul_u32_u24_e32 v39, 0x110, v38
	s_sub_i32 s0, s0, s7
	s_add_i32 s37, s0, 0xfffff000
	v_lshlrev_b32_e32 v66, 2, v34
	v_lshlrev_b32_e32 v68, 1, v38
	v_add_u32_e32 v76, v35, v36
	v_add_u32_e32 v77, v37, v39
	v_mov_b64_e32 v[72:73], v[70:71]
	v_readlane_b32 s50, v252, 6
	v_readlane_b32 s51, v252, 7
	s_mov_b32 s99, 0
	s_branch .LBB0_81

; #define LAS __attribute__((address_space(3)))
; __device__ __forceinline__ TItem titem(const Params& p, int l, int r, int lane) {
;     const float* W; half_t* WT; int N, ldt, koff = 0;
;     unsigned char* ws = p.ws;
;     const bool bf = (r < I_IN) ? INPROJ_BF16 : TAIL_BF16;
;     if (r < I_IN) { W = p.w_in + (size_t)l * DM * NIN; N = NIN; WT = (half_t*)(ws + WS_WIN + l * SZ_WIN); ldt = DM; }
;     else { r -= I_IN; N = DM;
;         if (r < I_SQ) { W = p.w_ret_o + (size_t)l * DM * DM; WT = (half_t*)(ws + WS_WMRG + l * SZ_WMRG); ldt = 4096; }
;         else if (r < 2 * I_SQ) { r -= I_SQ; W = p.w_swa_o + (size_t)l * DM * DM; WT = (half_t*)(ws + WS_WMRG + l * SZ_WMRG); ldt = 4096; koff = 2048; }
;         else { r -= 2 * I_SQ; W = p.w_out + (size_t)l * DM * DM; WT = (half_t*)(ws + WS_WOUT + l * SZ_WOUT); ldt = DM; } }
;     const int nblk = N >> 6, kb = r / nblk, nb = r - kb * nblk, k0 = kb * 32, n0 = nb * 64;
;     TItem t; t.N = N; t.ldt = ldt; t.bf = bf;
;     t.src = W + (size_t)(k0 + (lane >> 4)) * N + n0 + (lane & 15) * 4;
;     t.dst = WT + (size_t)(n0 + (lane >> 2)) * ldt + koff + k0 + 8 * (lane & 3);
;     return t;
; }
; __device__ __forceinline__ void tload(const TItem& t, f32x4 (&v)[8]) {
; #pragma unroll
;     for (int i = 0; i < 8; ++i) v[i] = *(const f32x4*)(t.src + (size_t)(4 * i) * t.N);
; __device__ __forceinline__ void tstore(const TItem& t, const f32x4 (&v)[8], LAS float* scr, int lane) {
;     const int rr = lane >> 4, c4 = (lane & 15) * 4;
; #pragma unroll
;     for (int i = 0; i < 8; ++i) *(LAS f32x4*)(scr + (4 * i + rr) * 68 + c4) = v[i];
; __device__ __forceinline__ void convert_range(const Params& p, int l, int lo, int hi, LAS float* scr, int gw, int NGW, int lane) {
;     ...
;         const int itn = it + NGW; const bool more = itn < hi;
;         TItem tn = tc;
;         if (more) { tn = titem(p, l, itn, lane); tload(tn, nxt); }
;         tstore(tc, cur, scr, lane);
.LBB0_90:
	s_add_u32 s26, s66, s26
	s_addc_u32 s27, s67, s27
	s_lshr_b32 s30, s7, 6
	v_cvt_f32_ubyte0_e32 v34, s30
	v_rcp_iflag_f32_e32 v34, v34
	s_sub_i32 s41, 0, s30
	s_abs_i32 s39, s0
	s_ashr_i32 s31, s0, 31
	v_mul_f32_e32 v34, 0x4f7ffffe, v34
	v_cvt_u32_f32_e32 v34, v34
	s_nop 0
	v_readfirstlane_b32 s42, v34
	s_mul_i32 s41, s41, s42
	s_mul_hi_u32 s41, s42, s41
	s_add_i32 s42, s42, s41
	s_mul_hi_u32 s41, s39, s42
	s_mul_i32 s42, s41, s30
	s_sub_i32 s39, s39, s42
	s_add_i32 s43, s41, 1
	s_sub_i32 s42, s39, s30
	s_cmp_ge_u32 s39, s30
	s_cselect_b32 s41, s43, s41
	s_cselect_b32 s39, s42, s39
	s_add_i32 s42, s41, 1
	s_cmp_ge_u32 s39, s30
	s_cselect_b32 s39, s42, s41
	s_xor_b32 s39, s39, s31
	s_sub_i32 s31, s39, s31
	s_mul_i32 s30, s31, s30
	s_sub_i32 s0, s0, s30
	s_lshl_b32 s30, s31, 5
	v_or_b32_e32 v34, s30, v74
	s_lshl_b32 s42, s0, 6
	v_mad_i64_i32 v[34:35], s[44:45], v34, s7, 0
	v_lshl_add_u64 v[34:35], v[34:35], 2, s[24:25]
	s_ashr_i32 s43, s42, 31
	v_lshl_add_u64 v[34:35], s[42:43], 2, v[34:35]
	v_lshl_add_u64 v[34:35], v[34:35], 0, v[66:67]
	s_lshl_b32 s0, s7, 4
	v_lshl_add_u64 v[42:43], v[34:35], 0, s[0:1]
	global_load_dwordx4 v[38:41], v[34:35], off
	s_nop 0
	global_load_dwordx4 v[34:37], v[42:43], off
	v_lshl_add_u64 v[42:43], v[42:43], 0, s[0:1]
	v_lshl_add_u64 v[50:51], v[42:43], 0, s[0:1]
	global_load_dwordx4 v[46:49], v[42:43], off
	s_nop 0
	global_load_dwordx4 v[42:45], v[50:51], off
	v_lshl_add_u64 v[50:51], v[50:51], 0, s[0:1]
	v_lshl_add_u64 v[58:59], v[50:51], 0, s[0:1]
	global_load_dwordx4 v[54:57], v[50:51], off
	s_nop 0
	global_load_dwordx4 v[50:53], v[58:59], off
	v_lshl_add_u64 v[58:59], v[58:59], 0, s[0:1]
	v_lshl_add_u64 v[60:61], v[58:59], 0, s[0:1]
	global_load_dwordx4 v[62:65], v[58:59], off
	s_nop 0
	global_load_dwordx4 v[58:61], v[60:61], off
	v_or_b32_e32 v69, s42, v75
	s_mul_i32 s0, s43, s38
	v_mad_u64_u32 v[72:73], s[24:25], v69, s38, 0
	v_add_u32_e32 v73, s0, v73
	v_lshl_add_u64 v[72:73], v[72:73], 1, s[26:27]
	v_lshl_add_u64 v[72:73], s[20:21], 1, v[72:73]
	s_ashr_i32 s31, s30, 31
	v_lshl_add_u64 v[72:73], s[30:31], 1, v[72:73]
	v_mov_b32_e32 v69, v67
	v_lshl_add_u64 v[72:73], v[72:73], 0, v[68:69]
	s_cmp_eq_u32 s99, 0
	s_cbranch_scc1 .Lcv_first_81
	s_waitcnt vmcnt(19)
	ds_write_b128 v76, v[26:29] offset:32768
	s_waitcnt vmcnt(18)
	ds_write_b128 v76, v[22:25] offset:33856
	s_waitcnt vmcnt(17)
	ds_write_b128 v76, v[18:21] offset:34944
	s_waitcnt vmcnt(16)
	ds_write_b128 v76, v[14:17] offset:36032
	s_waitcnt vmcnt(15)
	ds_write_b128 v76, v[10:13] offset:37120
	s_waitcnt vmcnt(14)
	ds_write_b128 v76, v[6:9] offset:38208
	s_waitcnt vmcnt(13)
	ds_write_b128 v76, v[2:5] offset:39296
	s_waitcnt vmcnt(12)
	ds_write_b128 v76, v[30:33] offset:40384
	s_branch .Lcv_join_81

; #define LAS __attribute__((address_space(3)))
; __device__ __forceinline__ void tstore(const TItem& t, const f32x4 (&v)[8], LAS float* scr, int lane) {
;     ...
;     asm volatile("s_waitcnt lgkmcnt(0)" ::: "memory");
;     const int c = lane & 3;
; #pragma unroll
;     for (int j = 0; j < 4; ++j) { const int n = (lane >> 2) + 16 * j; const LAS float* s = scr + (8 * c) * 68 + n;
;         h8 o;
; #pragma unroll
;         for (int e = 0; e < 8; ++e) o[e] = op16(s[e * 68], t.bf);
;         *(h8*)(t.dst + (size_t)(16 * j) * t.ldt) = o; }
;     asm volatile("s_waitcnt lgkmcnt(0)" ::: "memory");
; }
; __device__ __forceinline__ void convert_range(const Params& p, int l, int lo, int hi, LAS float* scr, int gw, int NGW, int lane) {
;     ...
;         tstore(tc, cur, scr, lane);
;         if (!more) break;
; #pragma unroll
;         for (int i = 0; i < 8; ++i) cur[i] = nxt[i];
;         tc = tn; it = itn;
.Lcv_join_81:
	s_waitcnt lgkmcnt(0)
	v_add_u32_e32 v22, 0x8000, v77
	v_add_u32_e32 v23, 0x8400, v77
	ds_read2_b32 v[6:7], v22 offset1:16
	ds_read2_b32 v[8:9], v22 offset0:136 offset1:152
	ds_read2_b32 v[10:11], v23 offset0:16 offset1:32
	ds_read2_b32 v[12:13], v23 offset0:152 offset1:168
	ds_read2_b32 v[14:15], v23 offset0:220 offset1:236
	ds_read2_b32 v[16:17], v23 offset0:84 offset1:100
	ds_read2_b32 v[18:19], v22 offset0:204 offset1:220
	ds_read2_b32 v[20:21], v22 offset0:68 offset1:84
	s_mov_b32 s7, s1
	s_waitcnt lgkmcnt(3)
	v_cvt_pk_bf16_f32 v5, v12, v14
	s_waitcnt lgkmcnt(2)
	v_cvt_pk_bf16_f32 v4, v10, v16
	s_waitcnt lgkmcnt(1)
	v_cvt_pk_bf16_f32 v3, v8, v18
	s_waitcnt lgkmcnt(0)
	v_cvt_pk_bf16_f32 v2, v6, v20
	global_store_dwordx4 v[70:71], v[2:5], off
	v_add_u32_e32 v16, 0x8600, v77
	s_lshl_b64 s[6:7], s[6:7], 5
	v_cvt_pk_bf16_f32 v5, v13, v15
	v_cvt_pk_bf16_f32 v4, v11, v17
	v_cvt_pk_bf16_f32 v3, v9, v19
	v_cvt_pk_bf16_f32 v2, v7, v21
	ds_read2_b32 v[8:9], v22 offset0:32 offset1:48
	ds_read2_b32 v[10:11], v22 offset0:168 offset1:184
	ds_read2_b32 v[12:13], v23 offset0:48 offset1:64
	ds_read2_b32 v[14:15], v23 offset0:184 offset1:200
	ds_read2_b32 v[16:17], v16 offset0:124 offset1:140
	ds_read2_b32 v[18:19], v23 offset0:116 offset1:132
	ds_read2_b32 v[20:21], v22 offset0:236 offset1:252
	ds_read2_b32 v[22:23], v22 offset0:100 offset1:116
	v_lshl_add_u64 v[6:7], v[70:71], 0, s[6:7]
	global_store_dwordx4 v[6:7], v[2:5], off
	v_lshl_add_u64 v[6:7], v[6:7], 0, s[6:7]
	s_andn2_b64 vcc, exec, s[18:19]
	s_waitcnt lgkmcnt(3)
	v_cvt_pk_bf16_f32 v5, v14, v16
	s_waitcnt lgkmcnt(2)
	v_cvt_pk_bf16_f32 v4, v12, v18
	s_waitcnt lgkmcnt(1)
	v_cvt_pk_bf16_f32 v3, v10, v20
	s_waitcnt lgkmcnt(0)
	v_cvt_pk_bf16_f32 v2, v8, v22
	global_store_dwordx4 v[6:7], v[2:5], off
	v_lshl_add_u64 v[6:7], v[6:7], 0, s[6:7]
	s_mov_b64 s[6:7], -1
	v_cvt_pk_bf16_f32 v5, v15, v17
	v_cvt_pk_bf16_f32 v4, v13, v19
	v_cvt_pk_bf16_f32 v3, v11, v21
	v_cvt_pk_bf16_f32 v2, v9, v23
	global_store_dwordx4 v[6:7], v[2:5], off
	s_waitcnt lgkmcnt(0)
	s_cbranch_vccnz .LBB0_80
	s_waitcnt vmcnt(4)
	s_mov_b32 s99, 1
	s_add_i32 s37, s37, s34
	s_mov_b64 s[6:7], 0
	v_mov_b32_e32 v5, v65
	v_mov_b32_e32 v4, v64
	v_mov_b32_e32 v3, v63
	v_mov_b32_e32 v2, v62
	v_mov_b32_e32 v9, v53
	v_mov_b32_e32 v8, v52
	v_mov_b32_e32 v7, v51
	v_mov_b32_e32 v6, v50
	v_mov_b32_e32 v13, v57
	v_mov_b32_e32 v12, v56
	v_mov_b32_e32 v11, v55
	v_mov_b32_e32 v10, v54
	v_mov_b32_e32 v17, v45
	v_mov_b32_e32 v16, v44
	v_mov_b32_e32 v15, v43
	v_mov_b32_e32 v14, v42
	v_mov_b32_e32 v21, v49
	v_mov_b32_e32 v20, v48
	v_mov_b32_e32 v19, v47
	v_mov_b32_e32 v18, v46
	v_mov_b32_e32 v25, v37
	v_mov_b32_e32 v24, v36
	v_mov_b32_e32 v23, v35
	v_mov_b32_e32 v22, v34
	v_mov_b32_e32 v29, v41
	v_mov_b32_e32 v28, v40
	v_mov_b32_e32 v27, v39
	v_mov_b32_e32 v26, v38
	s_branch .LBB0_80

; #define LAS __attribute__((address_space(3)))
; __device__ __forceinline__ TItem titem(const Params& p, int l, int r, int lane) {
;     const float* W; half_t* WT; int N, ldt, koff = 0;
;     unsigned char* ws = p.ws;
;     const bool bf = (r < I_IN) ? INPROJ_BF16 : TAIL_BF16;
;     if (r < I_IN) { W = p.w_in + (size_t)l * DM * NIN; N = NIN; WT = (half_t*)(ws + WS_WIN + l * SZ_WIN); ldt = DM; }
;     else { r -= I_IN; N = DM;
;         if (r < I_SQ) { W = p.w_ret_o + (size_t)l * DM * DM; WT = (half_t*)(ws + WS_WMRG + l * SZ_WMRG); ldt = 4096; }
;         else if (r < 2 * I_SQ) { r -= I_SQ; W = p.w_swa_o + (size_t)l * DM * DM; WT = (half_t*)(ws + WS_WMRG + l * SZ_WMRG); ldt = 4096; koff = 2048; }
;         else { r -= 2 * I_SQ; W = p.w_out + (size_t)l * DM * DM; WT = (half_t*)(ws + WS_WOUT + l * SZ_WOUT); ldt = DM; } }
;     const int nblk = N >> 6, kb = r / nblk, nb = r - kb * nblk, k0 = kb * 32, n0 = nb * 64;
;     TItem t; t.N = N; t.ldt = ldt; t.bf = bf;
;     t.src = W + (size_t)(k0 + (lane >> 4)) * N + n0 + (lane & 15) * 4;
;     t.dst = WT + (size_t)(n0 + (lane >> 2)) * ldt + koff + k0 + 8 * (lane & 3);
;     return t;
; }
; __device__ __forceinline__ void tload(const TItem& t, f32x4 (&v)[8]) {
; #pragma unroll
;     for (int i = 0; i < 8; ++i) v[i] = *(const f32x4*)(t.src + (size_t)(4 * i) * t.N);
; __device__ __forceinline__ void convert_range(const Params& p, int l, int lo, int hi, LAS float* scr, int gw, int NGW, int lane) {
;     int it = lo + gw;
;     if (it >= hi) return;
;     f32x4 cur[8], nxt[8];
;     TItem tc = titem(p, l, it, lane);
;     tload(tc, cur);
.LBB0_105:
	s_add_u32 s12, s12, s18
	s_addc_u32 s13, s13, s19
	s_add_u32 s14, s66, s14
	s_addc_u32 s15, s67, s15
	s_lshr_b32 s11, s9, 6
	v_cvt_f32_ubyte0_e32 v2, s11
	v_rcp_iflag_f32_e32 v2, v2
	s_sub_i32 s20, 0, s11
	s_abs_i32 s19, s0
	s_ashr_i32 s18, s0, 31
	v_mul_f32_e32 v2, 0x4f7ffffe, v2
	v_cvt_u32_f32_e32 v2, v2
	v_lshrrev_b32_e32 v74, 4, v1
	v_lshlrev_b32_e32 v4, 2, v1
	v_lshrrev_b32_e32 v75, 2, v1
	v_readfirstlane_b32 s21, v2
	s_mul_i32 s20, s20, s21
	s_mul_hi_u32 s20, s21, s20
	s_add_i32 s21, s21, s20
	s_mul_hi_u32 s20, s19, s21
	s_mul_i32 s21, s20, s11
	s_sub_i32 s19, s19, s21
	s_add_i32 s24, s20, 1
	s_sub_i32 s21, s19, s11
	s_cmp_ge_u32 s19, s11
	s_cselect_b32 s20, s24, s20
	s_cselect_b32 s19, s21, s19
	s_add_i32 s21, s20, 1
	s_cmp_ge_u32 s19, s11
	s_cselect_b32 s19, s21, s20
	s_xor_b32 s19, s19, s18
	s_sub_i32 s18, s19, s18
	s_mul_i32 s11, s18, s11
	s_sub_i32 s0, s0, s11
	s_lshl_b32 s18, s18, 5
	s_lshl_b32 s20, s0, 6
	v_or_b32_e32 v2, s18, v74
	v_mad_i64_i32 v[2:3], s[24:25], v2, s9, 0
	v_and_b32_e32 v34, 60, v4
	v_or_b32_e32 v4, s20, v75
	v_lshl_add_u64 v[2:3], v[2:3], 2, s[12:13]
	s_ashr_i32 s21, s20, 31
	v_mad_i64_i32 v[4:5], s[12:13], v4, s8, 0
	v_lshl_add_u64 v[2:3], s[20:21], 2, v[2:3]
	v_mov_b32_e32 v67, 0
	v_lshlrev_b32_e32 v66, 2, v34
	v_lshl_add_u64 v[4:5], v[4:5], 1, s[14:15]
	s_lshl_b32 s0, s10, 1
	v_lshl_add_u64 v[2:3], v[2:3], 0, v[66:67]
	v_lshl_add_u64 v[36:37], v[4:5], 0, s[0:1]
	s_lshl_b32 s0, s9, 4
	v_lshl_add_u64 v[4:5], v[2:3], 0, s[0:1]
	global_load_dwordx4 v[26:29], v[2:3], off
	global_load_dwordx4 v[22:25], v[4:5], off
	v_lshl_add_u64 v[2:3], v[4:5], 0, s[0:1]
	v_lshl_add_u64 v[4:5], v[2:3], 0, s[0:1]
	global_load_dwordx4 v[18:21], v[2:3], off
	global_load_dwordx4 v[14:17], v[4:5], off
	v_lshl_add_u64 v[2:3], v[4:5], 0, s[0:1]
	v_lshl_add_u64 v[4:5], v[2:3], 0, s[0:1]
	v_lshl_add_u64 v[30:31], v[4:5], 0, s[0:1]
	global_load_dwordx4 v[10:13], v[2:3], off
	global_load_dwordx4 v[6:9], v[4:5], off
	v_readlane_b32 s40, v252, 0
	global_load_dwordx4 v[2:5], v[30:31], off
	v_lshl_add_u64 v[30:31], v[30:31], 0, s[0:1]
	global_load_dwordx4 v[30:33], v[30:31], off
	s_ashr_i32 s19, s18, 31
	v_readlane_b32 s44, v252, 4
	v_readlane_b32 s45, v252, 5
	s_add_u32 s10, s44, 0x2000000
	v_readlane_b32 s42, v252, 2
	s_addc_u32 s11, s45, 0
	v_readlane_b32 s43, v252, 3
	s_add_u32 s12, s42, 0x2000000
	v_lshlrev_b32_e32 v35, 3, v1
	s_addc_u32 s13, s43, 0
	v_and_b32_e32 v38, 24, v35
	v_readlane_b32 s41, v252, 1
	s_add_u32 s14, s40, 0x2000000
	v_lshl_add_u64 v[36:37], s[18:19], 1, v[36:37]
	v_lshlrev_b32_e32 v40, 1, v38
	v_mov_b32_e32 v41, v67
	s_addc_u32 s15, s41, 0
	v_lshl_add_u64 v[70:71], v[36:37], 0, v[40:41]
	v_and_b32_e32 v37, 60, v1
	s_add_u32 s18, s90, 0xf000000
	v_add_u32_e32 v35, s36, v66
	v_mul_u32_u24_e32 v36, 0x110, v74
	v_add_u32_e32 v37, s36, v37
	v_mul_u32_u24_e32 v39, 0x110, v38
	s_addc_u32 s19, s91, 0
	s_add_i32 s0, s37, s68
	s_add_i32 s39, s0, 0xfffff000
	v_lshlrev_b32_e32 v66, 2, v34
	v_lshlrev_b32_e32 v68, 1, v38
	v_add_u32_e32 v76, v35, v36
	v_add_u32_e32 v77, v37, v39
	s_mov_b32 s40, s38
	v_mov_b64_e32 v[72:73], v[70:71]
	v_readlane_b32 s46, v252, 6
	v_readlane_b32 s47, v252, 7
	s_mov_b32 s99, 0
	s_branch .LBB0_107

; #define LAS __attribute__((address_space(3)))
; __device__ __forceinline__ TItem titem(const Params& p, int l, int r, int lane) {
;     const float* W; half_t* WT; int N, ldt, koff = 0;
;     unsigned char* ws = p.ws;
;     const bool bf = (r < I_IN) ? INPROJ_BF16 : TAIL_BF16;
;     if (r < I_IN) { W = p.w_in + (size_t)l * DM * NIN; N = NIN; WT = (half_t*)(ws + WS_WIN + l * SZ_WIN); ldt = DM; }
;     else { r -= I_IN; N = DM;
;         if (r < I_SQ) { W = p.w_ret_o + (size_t)l * DM * DM; WT = (half_t*)(ws + WS_WMRG + l * SZ_WMRG); ldt = 4096; }
;         else if (r < 2 * I_SQ) { r -= I_SQ; W = p.w_swa_o + (size_t)l * DM * DM; WT = (half_t*)(ws + WS_WMRG + l * SZ_WMRG); ldt = 4096; koff = 2048; }
;         else { r -= 2 * I_SQ; W = p.w_out + (size_t)l * DM * DM; WT = (half_t*)(ws + WS_WOUT + l * SZ_WOUT); ldt = DM; } }
;     const int nblk = N >> 6, kb = r / nblk, nb = r - kb * nblk, k0 = kb * 32, n0 = nb * 64;
;     TItem t; t.N = N; t.ldt = ldt; t.bf = bf;
;     t.src = W + (size_t)(k0 + (lane >> 4)) * N + n0 + (lane & 15) * 4;
;     t.dst = WT + (size_t)(n0 + (lane >> 2)) * ldt + koff + k0 + 8 * (lane & 3);
;     return t;
; }
; __device__ __forceinline__ void tload(const TItem& t, f32x4 (&v)[8]) {
; #pragma unroll
;     for (int i = 0; i < 8; ++i) v[i] = *(const f32x4*)(t.src + (size_t)(4 * i) * t.N);
; __device__ __forceinline__ void tstore(const TItem& t, const f32x4 (&v)[8], LAS float* scr, int lane) {
;     const int rr = lane >> 4, c4 = (lane & 15) * 4;
; #pragma unroll
;     for (int i = 0; i < 8; ++i) *(LAS f32x4*)(scr + (4 * i + rr) * 68 + c4) = v[i];
; __device__ __forceinline__ void convert_range(const Params& p, int l, int lo, int hi, LAS float* scr, int gw, int NGW, int lane) {
;     ...
;         const int itn = it + NGW; const bool more = itn < hi;
;         TItem tn = tc;
;         if (more) { tn = titem(p, l, itn, lane); tload(tn, nxt); }
;         tstore(tc, cur, scr, lane);
.LBB0_116:
	s_add_u32 s30, s66, s30
	s_addc_u32 s31, s67, s31
	s_lshr_b32 s34, s9, 6
	v_cvt_f32_ubyte0_e32 v34, s34
	v_rcp_iflag_f32_e32 v34, v34
	s_sub_i32 s43, 0, s34
	s_abs_i32 s42, s0
	s_ashr_i32 s35, s0, 31
	v_mul_f32_e32 v34, 0x4f7ffffe, v34
	v_cvt_u32_f32_e32 v34, v34
	s_nop 0
	v_readfirstlane_b32 s44, v34
	s_mul_i32 s43, s43, s44
	s_mul_hi_u32 s43, s44, s43
	s_add_i32 s44, s44, s43
	s_mul_hi_u32 s43, s42, s44
	s_mul_i32 s44, s43, s34
	s_sub_i32 s42, s42, s44
	s_add_i32 s45, s43, 1
	s_sub_i32 s44, s42, s34
	s_cmp_ge_u32 s42, s34
	s_cselect_b32 s43, s45, s43
	s_cselect_b32 s42, s44, s42
	s_add_i32 s44, s43, 1
	s_cmp_ge_u32 s42, s34
	s_cselect_b32 s42, s44, s43
	s_xor_b32 s42, s42, s35
	s_sub_i32 s35, s42, s35
	s_mul_i32 s34, s35, s34
	s_sub_i32 s0, s0, s34
	s_lshl_b32 s34, s35, 5
	v_or_b32_e32 v34, s34, v74
	s_lshl_b32 s42, s0, 6
	v_mad_i64_i32 v[34:35], s[44:45], v34, s9, 0
	v_lshl_add_u64 v[34:35], v[34:35], 2, s[26:27]
	s_ashr_i32 s43, s42, 31
	v_lshl_add_u64 v[34:35], s[42:43], 2, v[34:35]
	v_lshl_add_u64 v[34:35], v[34:35], 0, v[66:67]
	s_lshl_b32 s0, s9, 4
	v_lshl_add_u64 v[42:43], v[34:35], 0, s[0:1]
	global_load_dwordx4 v[38:41], v[34:35], off
	s_nop 0
	global_load_dwordx4 v[34:37], v[42:43], off
	v_lshl_add_u64 v[42:43], v[42:43], 0, s[0:1]
	v_lshl_add_u64 v[50:51], v[42:43], 0, s[0:1]
	global_load_dwordx4 v[46:49], v[42:43], off
	s_nop 0
	global_load_dwordx4 v[42:45], v[50:51], off
	v_lshl_add_u64 v[50:51], v[50:51], 0, s[0:1]
	v_lshl_add_u64 v[58:59], v[50:51], 0, s[0:1]
	global_load_dwordx4 v[54:57], v[50:51], off
	s_nop 0
	global_load_dwordx4 v[50:53], v[58:59], off
	v_lshl_add_u64 v[58:59], v[58:59], 0, s[0:1]
	v_lshl_add_u64 v[60:61], v[58:59], 0, s[0:1]
	global_load_dwordx4 v[62:65], v[58:59], off
	s_nop 0
	global_load_dwordx4 v[58:61], v[60:61], off
	v_or_b32_e32 v69, s42, v75
	s_mul_i32 s0, s43, s41
	v_mad_u64_u32 v[72:73], s[26:27], v69, s41, 0
	v_add_u32_e32 v73, s0, v73
	v_lshl_add_u64 v[72:73], v[72:73], 1, s[30:31]
	v_lshl_add_u64 v[72:73], s[24:25], 1, v[72:73]
	s_ashr_i32 s35, s34, 31
	v_lshl_add_u64 v[72:73], s[34:35], 1, v[72:73]
	v_mov_b32_e32 v69, v67
	v_lshl_add_u64 v[72:73], v[72:73], 0, v[68:69]
	s_cmp_eq_u32 s99, 0
	s_cbranch_scc1 .Lcv_first_107
	s_waitcnt vmcnt(19)
	ds_write_b128 v76, v[26:29] offset:32768
	s_waitcnt vmcnt(18)
	ds_write_b128 v76, v[22:25] offset:33856
	s_waitcnt vmcnt(17)
	ds_write_b128 v76, v[18:21] offset:34944
	s_waitcnt vmcnt(16)
	ds_write_b128 v76, v[14:17] offset:36032
	s_waitcnt vmcnt(15)
	ds_write_b128 v76, v[10:13] offset:37120
	s_waitcnt vmcnt(14)
	ds_write_b128 v76, v[6:9] offset:38208
	s_waitcnt vmcnt(13)
	ds_write_b128 v76, v[2:5] offset:39296
	s_waitcnt vmcnt(12)
	ds_write_b128 v76, v[30:33] offset:40384
	s_branch .Lcv_join_107

; #define LAS __attribute__((address_space(3)))
; __device__ __forceinline__ void tstore(const TItem& t, const f32x4 (&v)[8], LAS float* scr, int lane) {
;     ...
;     asm volatile("s_waitcnt lgkmcnt(0)" ::: "memory");
;     const int c = lane & 3;
; #pragma unroll
;     for (int j = 0; j < 4; ++j) { const int n = (lane >> 2) + 16 * j; const LAS float* s = scr + (8 * c) * 68 + n;
;         h8 o;
; #pragma unroll
;         for (int e = 0; e < 8; ++e) o[e] = op16(s[e * 68], t.bf);
;         *(h8*)(t.dst + (size_t)(16 * j) * t.ldt) = o; }
;     asm volatile("s_waitcnt lgkmcnt(0)" ::: "memory");
; }
; __device__ __forceinline__ void convert_range(const Params& p, int l, int lo, int hi, LAS float* scr, int gw, int NGW, int lane) {
;     ...
;         tstore(tc, cur, scr, lane);
;         if (!more) break;
; #pragma unroll
;         for (int i = 0; i < 8; ++i) cur[i] = nxt[i];
;         tc = tn; it = itn;
.Lcv_join_107:
	s_waitcnt lgkmcnt(0)
	v_add_u32_e32 v22, 0x8000, v77
	v_add_u32_e32 v23, 0x8400, v77
	ds_read2_b32 v[6:7], v22 offset1:16
	ds_read2_b32 v[8:9], v22 offset0:136 offset1:152
	ds_read2_b32 v[10:11], v23 offset0:16 offset1:32
	ds_read2_b32 v[12:13], v23 offset0:152 offset1:168
	ds_read2_b32 v[14:15], v23 offset0:220 offset1:236
	ds_read2_b32 v[16:17], v23 offset0:84 offset1:100
	ds_read2_b32 v[18:19], v22 offset0:204 offset1:220
	ds_read2_b32 v[20:21], v22 offset0:68 offset1:84
	s_mov_b32 s9, s1
	s_waitcnt lgkmcnt(3)
	v_cvt_pk_bf16_f32 v5, v12, v14
	s_waitcnt lgkmcnt(2)
	v_cvt_pk_bf16_f32 v4, v10, v16
	s_waitcnt lgkmcnt(1)
	v_cvt_pk_bf16_f32 v3, v8, v18
	s_waitcnt lgkmcnt(0)
	v_cvt_pk_bf16_f32 v2, v6, v20
	global_store_dwordx4 v[70:71], v[2:5], off
	v_add_u32_e32 v16, 0x8600, v77
	s_lshl_b64 s[8:9], s[8:9], 5
	v_cvt_pk_bf16_f32 v5, v13, v15
	v_cvt_pk_bf16_f32 v4, v11, v17
	v_cvt_pk_bf16_f32 v3, v9, v19
	v_cvt_pk_bf16_f32 v2, v7, v21
	ds_read2_b32 v[8:9], v22 offset0:32 offset1:48
	ds_read2_b32 v[10:11], v22 offset0:168 offset1:184
	ds_read2_b32 v[12:13], v23 offset0:48 offset1:64
	ds_read2_b32 v[14:15], v23 offset0:184 offset1:200
	ds_read2_b32 v[16:17], v16 offset0:124 offset1:140
	ds_read2_b32 v[18:19], v23 offset0:116 offset1:132
	ds_read2_b32 v[20:21], v22 offset0:236 offset1:252
	ds_read2_b32 v[22:23], v22 offset0:100 offset1:116
	v_lshl_add_u64 v[6:7], v[70:71], 0, s[8:9]
	global_store_dwordx4 v[6:7], v[2:5], off
	v_lshl_add_u64 v[6:7], v[6:7], 0, s[8:9]
	s_andn2_b64 vcc, exec, s[20:21]
	s_waitcnt lgkmcnt(3)
	v_cvt_pk_bf16_f32 v5, v14, v16
	s_waitcnt lgkmcnt(2)
	v_cvt_pk_bf16_f32 v4, v12, v18
	s_waitcnt lgkmcnt(1)
	v_cvt_pk_bf16_f32 v3, v10, v20
	s_waitcnt lgkmcnt(0)
	v_cvt_pk_bf16_f32 v2, v8, v22
	global_store_dwordx4 v[6:7], v[2:5], off
	v_lshl_add_u64 v[6:7], v[6:7], 0, s[8:9]
	s_mov_b64 s[8:9], -1
	v_cvt_pk_bf16_f32 v5, v15, v17
	v_cvt_pk_bf16_f32 v4, v13, v19
	v_cvt_pk_bf16_f32 v3, v11, v21
	v_cvt_pk_bf16_f32 v2, v9, v23
	global_store_dwordx4 v[6:7], v[2:5], off
	s_waitcnt lgkmcnt(0)
	s_cbranch_vccnz .LBB0_106
	s_waitcnt vmcnt(4)
	s_mov_b32 s99, 1
	s_add_i32 s39, s39, s68
	s_mov_b64 s[8:9], 0
	v_mov_b32_e32 v5, v65
	v_mov_b32_e32 v4, v64
	v_mov_b32_e32 v3, v63
	v_mov_b32_e32 v2, v62
	v_mov_b32_e32 v9, v53
	v_mov_b32_e32 v8, v52
	v_mov_b32_e32 v7, v51
	v_mov_b32_e32 v6, v50
	v_mov_b32_e32 v13, v57
	v_mov_b32_e32 v12, v56
	v_mov_b32_e32 v11, v55
	v_mov_b32_e32 v10, v54
	v_mov_b32_e32 v17, v45
	v_mov_b32_e32 v16, v44
	v_mov_b32_e32 v15, v43
	v_mov_b32_e32 v14, v42
	v_mov_b32_e32 v21, v49
	v_mov_b32_e32 v20, v48
	v_mov_b32_e32 v19, v47
	v_mov_b32_e32 v18, v46
	v_mov_b32_e32 v25, v37
	v_mov_b32_e32 v24, v36
	v_mov_b32_e32 v23, v35
	v_mov_b32_e32 v22, v34
	v_mov_b32_e32 v29, v41
	v_mov_b32_e32 v28, v40
	v_mov_b32_e32 v27, v39
	v_mov_b32_e32 v26, v38
	s_branch .LBB0_106

; #define LAS __attribute__((address_space(3)))
; __global__ void __launch_bounds__(512, 2) hybrid_fwd(Params p) {
;     extern __shared__ __attribute__((aligned(16))) unsigned char shm[];
;     LAS unsigned char* lds = (LAS unsigned char*)shm;
;     cg::grid_group grid = cg::this_grid();
;     const int tid = threadIdx.x, G = gridDim.x;
	.amdhsa_kernel _Z10hybrid_fwd6Params
		.amdhsa_group_segment_fixed_size 0
		.amdhsa_private_segment_fixed_size 0
		.amdhsa_kernarg_size 368
		.amdhsa_user_sgpr_count 2
		.amdhsa_user_sgpr_dispatch_ptr 0
		.amdhsa_user_sgpr_queue_ptr 0
		.amdhsa_user_sgpr_kernarg_segment_ptr 1
		.amdhsa_user_sgpr_dispatch_id 0
		.amdhsa_user_sgpr_kernarg_preload_length 0
		.amdhsa_user_sgpr_kernarg_preload_offset 0
		.amdhsa_user_sgpr_private_segment_size 0
		.amdhsa_uses_dynamic_stack 0
		.amdhsa_enable_private_segment 0
		.amdhsa_system_sgpr_workgroup_id_x 1
		.amdhsa_system_sgpr_workgroup_id_y 0
		.amdhsa_system_sgpr_workgroup_id_z 0
		.amdhsa_system_sgpr_workgroup_info 0
		.amdhsa_system_vgpr_workitem_id 2
		.amdhsa_next_free_vgpr 254
		.amdhsa_next_free_sgpr 100
		.amdhsa_accum_offset 256
		.amdhsa_reserve_vcc 1
		.amdhsa_float_round_mode_32 0
		.amdhsa_float_round_mode_16_64 0
		.amdhsa_float_denorm_mode_32 3
		.amdhsa_float_denorm_mode_16_64 3
		.amdhsa_dx10_clamp 1
		.amdhsa_ieee_mode 1
		.amdhsa_fp16_overflow 0
		.amdhsa_tg_split 0
		.amdhsa_exception_fp_ieee_invalid_op 0
		.amdhsa_exception_fp_denorm_src 0
		.amdhsa_exception_fp_ieee_div_zero 0
		.amdhsa_exception_fp_ieee_overflow 0
		.amdhsa_exception_fp_ieee_underflow 0
		.amdhsa_exception_fp_ieee_inexact 0
		.amdhsa_exception_int_div_zero 0
	.end_amdhsa_kernel

; #define LAS __attribute__((address_space(3)))
; __global__ void __launch_bounds__(512, 2) hybrid_fwd(Params p) {
;     extern __shared__ __attribute__((aligned(16))) unsigned char shm[];
;     LAS unsigned char* lds = (LAS unsigned char*)shm;
;     cg::grid_group grid = cg::this_grid();
;     const int tid = threadIdx.x, G = gridDim.x;
.Lfunc_end0:
	.size	_Z10hybrid_fwd6Params, .Lfunc_end0-_Z10hybrid_fwd6Params
	.set _Z10hybrid_fwd6Params.num_vgpr, 254
	.set _Z10hybrid_fwd6Params.num_agpr, 0
	.set _Z10hybrid_fwd6Params.numbered_sgpr, 100
	.set _Z10hybrid_fwd6Params.num_named_barrier, 0
	.set _Z10hybrid_fwd6Params.private_seg_size, 0
	.set _Z10hybrid_fwd6Params.uses_vcc, 1
	.set _Z10hybrid_fwd6Params.uses_flat_scratch, 0
	.set _Z10hybrid_fwd6Params.has_dyn_sized_stack, 0
	.set _Z10hybrid_fwd6Params.has_recursion, 0
	.set _Z10hybrid_fwd6Params.has_indirect_call, 0

; #define LAS __attribute__((address_space(3)))
; __global__ void __launch_bounds__(512, 2) hybrid_fwd(Params p) {
;     extern __shared__ __attribute__((aligned(16))) unsigned char shm[];
;     LAS unsigned char* lds = (LAS unsigned char*)shm;
;     cg::grid_group grid = cg::this_grid();
;     const int tid = threadIdx.x, G = gridDim.x;
amdhsa.kernels:
  - .agpr_count:     0
    .args:
      - .offset:         0
        .size:           112
        .value_kind:     by_value
      - .offset:         112
        .size:           4
        .value_kind:     hidden_block_count_x
      - .offset:         116
        .size:           4
        .value_kind:     hidden_block_count_y
      - .offset:         120
        .size:           4
        .value_kind:     hidden_block_count_z
      - .offset:         124
        .size:           2
        .value_kind:     hidden_group_size_x
      - .offset:         126
        .size:           2
        .value_kind:     hidden_group_size_y
      - .offset:         128
        .size:           2
        .value_kind:     hidden_group_size_z
      - .offset:         130
        .size:           2
        .value_kind:     hidden_remainder_x
      - .offset:         132
        .size:           2
        .value_kind:     hidden_remainder_y
      - .offset:         134
        .size:           2
        .value_kind:     hidden_remainder_z
      - .offset:         152
        .size:           8
        .value_kind:     hidden_global_offset_x
      - .offset:         160
        .size:           8
        .value_kind:     hidden_global_offset_y
      - .offset:         168
        .size:           8
        .value_kind:     hidden_global_offset_z
      - .offset:         176
        .size:           2
        .value_kind:     hidden_grid_dims
      - .offset:         200
        .size:           8
        .value_kind:     hidden_multigrid_sync_arg
      - .offset:         232
        .size:           4
        .value_kind:     hidden_dynamic_lds_size
    .group_segment_fixed_size: 0
    .kernarg_segment_align: 8
    .kernarg_segment_size: 368
    .language:       OpenCL C
    .language_version:
      - 2
      - 0
    .max_flat_workgroup_size: 512
    .name:           _Z10hybrid_fwd6Params
    .private_segment_fixed_size: 0
    .sgpr_count:     106
    .sgpr_spill_count: 197
    .symbol:         _Z10hybrid_fwd6Params.kd
    .uniform_work_group_size: 1
    .uses_dynamic_stack: false
    .vgpr_count:     254
    .vgpr_spill_count: 0
    .wavefront_size: 64
